# v042 plus per-phase pointer reloads replaced by reads of spare spill lanes filled once at kernel entry
# speedup vs baseline: 1.0056x; 1.0022x over previous
; __global__ void __launch_bounds__(512, 2) fwd_megakernel(Args a) {
	.amdhsa_kernel _Z14fwd_megakernel4Args
		.amdhsa_group_segment_fixed_size 0
		.amdhsa_private_segment_fixed_size 0
		.amdhsa_kernarg_size 432
		.amdhsa_user_sgpr_count 2
		.amdhsa_user_sgpr_dispatch_ptr 0
		.amdhsa_user_sgpr_queue_ptr 0
		.amdhsa_user_sgpr_kernarg_segment_ptr 1
		.amdhsa_user_sgpr_dispatch_id 0
		.amdhsa_user_sgpr_kernarg_preload_length 0
		.amdhsa_user_sgpr_kernarg_preload_offset 0
		.amdhsa_user_sgpr_private_segment_size 0
		.amdhsa_uses_dynamic_stack 0
		.amdhsa_enable_private_segment 0
		.amdhsa_system_sgpr_workgroup_id_x 1
		.amdhsa_system_sgpr_workgroup_id_y 0
		.amdhsa_system_sgpr_workgroup_id_z 0
		.amdhsa_system_sgpr_workgroup_info 0
		.amdhsa_system_vgpr_workitem_id 2
		.amdhsa_next_free_vgpr 256
		.amdhsa_next_free_sgpr 102
		.amdhsa_accum_offset 256
		.amdhsa_reserve_vcc 1
		.amdhsa_float_round_mode_32 0
		.amdhsa_float_round_mode_16_64 0
		.amdhsa_float_denorm_mode_32 3
		.amdhsa_float_denorm_mode_16_64 3
		.amdhsa_dx10_clamp 1
		.amdhsa_ieee_mode 1
		.amdhsa_fp16_overflow 0
		.amdhsa_tg_split 0
		.amdhsa_exception_fp_ieee_invalid_op 0
		.amdhsa_exception_fp_denorm_src 0
		.amdhsa_exception_fp_ieee_div_zero 0
		.amdhsa_exception_fp_ieee_overflow 0
		.amdhsa_exception_fp_ieee_underflow 0
		.amdhsa_exception_fp_ieee_inexact 0
		.amdhsa_exception_int_div_zero 0
	.end_amdhsa_kernel

; __global__ void __launch_bounds__(512, 2) fwd_megakernel(Args a) {
amdhsa.kernels:
  - .agpr_count:     0
    .args:
      - .offset:         0
        .size:           176
        .value_kind:     by_value
      - .offset:         176
        .size:           4
        .value_kind:     hidden_block_count_x
      - .offset:         180
        .size:           4
        .value_kind:     hidden_block_count_y
      - .offset:         184
        .size:           4
        .value_kind:     hidden_block_count_z
      - .offset:         188
        .size:           2
        .value_kind:     hidden_group_size_x
      - .offset:         190
        .size:           2
        .value_kind:     hidden_group_size_y
      - .offset:         192
        .size:           2
        .value_kind:     hidden_group_size_z
      - .offset:         194
        .size:           2
        .value_kind:     hidden_remainder_x
      - .offset:         196
        .size:           2
        .value_kind:     hidden_remainder_y
      - .offset:         198
        .size:           2
        .value_kind:     hidden_remainder_z
      - .offset:         216
        .size:           8
        .value_kind:     hidden_global_offset_x
      - .offset:         224
        .size:           8
        .value_kind:     hidden_global_offset_y
      - .offset:         232
        .size:           8
        .value_kind:     hidden_global_offset_z
      - .offset:         240
        .size:           2
        .value_kind:     hidden_grid_dims
      - .offset:         264
        .size:           8
        .value_kind:     hidden_multigrid_sync_arg
      - .offset:         296
        .size:           4
        .value_kind:     hidden_dynamic_lds_size
    .group_segment_fixed_size: 0
    .kernarg_segment_align: 8
    .kernarg_segment_size: 432
    .language:       OpenCL C
    .language_version:
      - 2
      - 0
    .max_flat_workgroup_size: 512
    .name:           _Z14fwd_megakernel4Args
    .private_segment_fixed_size: 0
    .sgpr_count:     108
    .sgpr_spill_count: 117
    .symbol:         _Z14fwd_megakernel4Args.kd
    .uniform_work_group_size: 1
    .uses_dynamic_stack: false
    .vgpr_count:     256
    .vgpr_spill_count: 0
    .wavefront_size: 64
